# attention epilogues: 16 dwordx2 output stores per lane paired into 8 dwordx4 stores via v_permlane32_swap (docs 7.3)
# speedup vs baseline: 1.0165x; 1.0161x over previous
; __device__ __forceinline__ unsigned cvt_pk_bf16(float lo, float hi) { f32x2 v = {lo, hi}; bf16x2_t b = __builtin_convertvector(v, bf16x2_t); return __builtin_bit_cast(unsigned, b); }
; template <int DQK, bool MOBA>
; __device__ __forceinline__ void attn_unit(const Args& A, int b, int h, int qb, lptr lds) {
;     ...
;     lrow += __shfl_xor(lrow, 32);
;     const float inv = 1.0f / lrow;
;     bf16* op = A.O + (size_t)qrow * 1024 + h * 128 + 4 * hi;
; #pragma unroll
;     for (int d = 0; d < 4; ++d)
; #pragma unroll
;         for (int a = 0; a < 4; ++a) {
;             u32x2 w; w.x = cvt_pk_bf16(o[d][4 * a] * inv, o[d][4 * a + 1] * inv); w.y = cvt_pk_bf16(o[d][4 * a + 2] * inv, o[d][4 * a + 3] * inv);
;             *(u32x2*)(op + 32 * d + 8 * a) = w;
;         }
.LBB0_755:
	ds_bpermute_b32 v66, v170, v184
	v_readlane_b32 s0, v253, 52
	v_lshlrev_b64 v[64:65], 11, v[160:161]
	v_readlane_b32 s1, v253, 53
	v_lshlrev_b32_e32 v180, 1, v176
	s_waitcnt lgkmcnt(0)
	v_add_f32_e32 v66, v184, v66
	v_lshl_add_u64 v[64:65], s[0:1], 0, v[64:65]
	v_div_scale_f32 v67, s[0:1], v66, v66, 1.0
	v_rcp_f32_e32 v68, v67
	v_div_scale_f32 v69, vcc, 1.0, v66, 1.0
	v_lshl_add_u64 v[64:65], s[46:47], 1, v[64:65]
	v_fma_f32 v70, -v67, v68, 1.0
	v_fmac_f32_e32 v68, v70, v68
	v_mul_f32_e32 v70, v69, v68
	v_fma_f32 v71, -v67, v70, v69
	v_fmac_f32_e32 v70, v71, v68
	v_fma_f32 v67, -v67, v70, v69
	v_div_fmas_f32 v67, v67, v68, v70
	v_div_fixup_f32 v66, v67, v66, 1.0
	v_lshl_add_u64 v[64:65], v[64:65], 0, v[180:181]
	v_lshl_add_u64 v[64:65], v[64:65], 0, v[180:181]
	v_pk_mul_f32 v[48:49], v[48:49], v[66:67] op_sel_hi:[1,0]
	v_pk_mul_f32 v[50:51], v[50:51], v[66:67] op_sel_hi:[1,0]
	v_pk_mul_f32 v[52:53], v[52:53], v[66:67] op_sel_hi:[1,0]
	v_pk_mul_f32 v[54:55], v[54:55], v[66:67] op_sel_hi:[1,0]
	v_cvt_pk_bf16_f32 v48, v48, v49
	v_cvt_pk_bf16_f32 v49, v50, v51
	v_cvt_pk_bf16_f32 v50, v52, v53
	v_cvt_pk_bf16_f32 v51, v54, v55
	v_pk_mul_f32 v[56:57], v[56:57], v[66:67] op_sel_hi:[1,0]
	v_pk_mul_f32 v[58:59], v[58:59], v[66:67] op_sel_hi:[1,0]
	v_pk_mul_f32 v[60:61], v[60:61], v[66:67] op_sel_hi:[1,0]
	v_pk_mul_f32 v[62:63], v[62:63], v[66:67] op_sel_hi:[1,0]
	v_permlane32_swap_b32 v48, v50
	v_permlane32_swap_b32 v49, v51
	global_store_dwordx4 v[64:65], v[48:51], off
	v_cvt_pk_bf16_f32 v52, v56, v57
	v_cvt_pk_bf16_f32 v53, v58, v59
	v_cvt_pk_bf16_f32 v54, v60, v61
	v_cvt_pk_bf16_f32 v55, v62, v63
	v_pk_mul_f32 v[32:33], v[32:33], v[66:67] op_sel_hi:[1,0]
	v_pk_mul_f32 v[34:35], v[34:35], v[66:67] op_sel_hi:[1,0]
	v_pk_mul_f32 v[36:37], v[36:37], v[66:67] op_sel_hi:[1,0]
	v_pk_mul_f32 v[38:39], v[38:39], v[66:67] op_sel_hi:[1,0]
	v_permlane32_swap_b32 v52, v54
	v_permlane32_swap_b32 v53, v55
	global_store_dwordx4 v[64:65], v[52:55], off offset:32
	v_cvt_pk_bf16_f32 v32, v32, v33
	v_cvt_pk_bf16_f32 v33, v34, v35
	v_cvt_pk_bf16_f32 v34, v36, v37
	v_cvt_pk_bf16_f32 v35, v38, v39
	v_pk_mul_f32 v[40:41], v[40:41], v[66:67] op_sel_hi:[1,0]
	v_pk_mul_f32 v[42:43], v[42:43], v[66:67] op_sel_hi:[1,0]
	v_pk_mul_f32 v[44:45], v[44:45], v[66:67] op_sel_hi:[1,0]
	v_pk_mul_f32 v[46:47], v[46:47], v[66:67] op_sel_hi:[1,0]
	v_permlane32_swap_b32 v32, v34
	v_permlane32_swap_b32 v33, v35
	global_store_dwordx4 v[64:65], v[32:35], off offset:64
	v_cvt_pk_bf16_f32 v36, v40, v41
	v_cvt_pk_bf16_f32 v37, v42, v43
	v_cvt_pk_bf16_f32 v38, v44, v45
	v_cvt_pk_bf16_f32 v39, v46, v47
	v_pk_mul_f32 v[16:17], v[16:17], v[66:67] op_sel_hi:[1,0]
	v_pk_mul_f32 v[18:19], v[18:19], v[66:67] op_sel_hi:[1,0]
	v_pk_mul_f32 v[20:21], v[20:21], v[66:67] op_sel_hi:[1,0]
	v_pk_mul_f32 v[22:23], v[22:23], v[66:67] op_sel_hi:[1,0]
	v_permlane32_swap_b32 v36, v38
	v_permlane32_swap_b32 v37, v39
	global_store_dwordx4 v[64:65], v[36:39], off offset:96
	v_cvt_pk_bf16_f32 v16, v16, v17
	v_cvt_pk_bf16_f32 v17, v18, v19
	v_cvt_pk_bf16_f32 v18, v20, v21
	v_cvt_pk_bf16_f32 v19, v22, v23
	v_pk_mul_f32 v[24:25], v[24:25], v[66:67] op_sel_hi:[1,0]
	v_pk_mul_f32 v[26:27], v[26:27], v[66:67] op_sel_hi:[1,0]
	v_pk_mul_f32 v[28:29], v[28:29], v[66:67] op_sel_hi:[1,0]
	v_pk_mul_f32 v[30:31], v[30:31], v[66:67] op_sel_hi:[1,0]
	v_permlane32_swap_b32 v16, v18
	v_permlane32_swap_b32 v17, v19
	global_store_dwordx4 v[64:65], v[16:19], off offset:128
	v_cvt_pk_bf16_f32 v20, v24, v25
	v_cvt_pk_bf16_f32 v21, v26, v27
	v_cvt_pk_bf16_f32 v22, v28, v29
	v_cvt_pk_bf16_f32 v23, v30, v31
	v_pk_mul_f32 v[0:1], v[0:1], v[66:67] op_sel_hi:[1,0]
	v_pk_mul_f32 v[2:3], v[2:3], v[66:67] op_sel_hi:[1,0]
	v_pk_mul_f32 v[4:5], v[4:5], v[66:67] op_sel_hi:[1,0]
	v_pk_mul_f32 v[6:7], v[6:7], v[66:67] op_sel_hi:[1,0]
	v_permlane32_swap_b32 v20, v22
	v_permlane32_swap_b32 v21, v23
	global_store_dwordx4 v[64:65], v[20:23], off offset:160
	v_cvt_pk_bf16_f32 v0, v0, v1
	v_cvt_pk_bf16_f32 v1, v2, v3
	v_cvt_pk_bf16_f32 v2, v4, v5
	v_cvt_pk_bf16_f32 v3, v6, v7
	v_pk_mul_f32 v[8:9], v[8:9], v[66:67] op_sel_hi:[1,0]
	v_pk_mul_f32 v[10:11], v[10:11], v[66:67] op_sel_hi:[1,0]
	v_pk_mul_f32 v[12:13], v[12:13], v[66:67] op_sel_hi:[1,0]
	v_pk_mul_f32 v[14:15], v[14:15], v[66:67] op_sel_hi:[1,0]
	v_permlane32_swap_b32 v0, v2
	v_permlane32_swap_b32 v1, v3
	global_store_dwordx4 v[64:65], v[0:3], off offset:192
	v_cvt_pk_bf16_f32 v4, v8, v9
	v_cvt_pk_bf16_f32 v5, v10, v11
	v_cvt_pk_bf16_f32 v6, v12, v13
	v_cvt_pk_bf16_f32 v7, v14, v15
	s_nop 1
	v_permlane32_swap_b32 v4, v6
	v_permlane32_swap_b32 v5, v7
	global_store_dwordx4 v[64:65], v[4:7], off offset:224
	s_add_i32 s53, s53, 1
	s_cmp_eq_u32 s53, 4
	s_cbranch_scc1 .LBB0_753

; __device__ __forceinline__ unsigned cvt_pk_bf16(float lo, float hi) { f32x2 v = {lo, hi}; bf16x2_t b = __builtin_convertvector(v, bf16x2_t); return __builtin_bit_cast(unsigned, b); }
; template <int DQK, bool MOBA>
; __device__ __forceinline__ void attn_unit(const Args& A, int b, int h, int qb, lptr lds) {
;     ...
;         __syncthreads();
;     }
;     lrow += __shfl_xor(lrow, 32);
;     const float inv = 1.0f / lrow;
;     bf16* op = A.O + (size_t)qrow * 1024 + h * 128 + 4 * hi;
; #pragma unroll
;     for (int d = 0; d < 4; ++d)
; #pragma unroll
;         for (int a = 0; a < 4; ++a) {
;             u32x2 w; w.x = cvt_pk_bf16(o[d][4 * a] * inv, o[d][4 * a + 1] * inv); w.y = cvt_pk_bf16(o[d][4 * a + 2] * inv, o[d][4 * a + 3] * inv);
;             *(u32x2*)(op + 32 * d + 8 * a) = w;
;         }
.LBB0_803:
	ds_bpermute_b32 v64, v196, v187
	v_lshlrev_b32_e32 v180, 1, v183
	s_waitcnt lgkmcnt(0)
	s_barrier
	v_add_f32_e32 v64, v187, v64
	v_div_scale_f32 v65, s[0:1], v64, v64, 1.0
	v_rcp_f32_e32 v66, v65
	v_div_scale_f32 v67, vcc, 1.0, v64, 1.0
	v_readlane_b32 s0, v253, 58
	v_fma_f32 v68, -v65, v66, 1.0
	v_fmac_f32_e32 v66, v68, v66
	v_mul_f32_e32 v68, v67, v66
	v_fma_f32 v69, -v65, v68, v67
	v_fmac_f32_e32 v68, v69, v66
	v_fma_f32 v65, -v65, v68, v67
	v_div_fmas_f32 v65, v65, v66, v68
	v_lshlrev_b64 v[66:67], 11, v[184:185]
	v_readlane_b32 s1, v253, 59
	v_div_fixup_f32 v64, v65, v64, 1.0
	v_lshl_add_u64 v[66:67], s[0:1], 0, v[66:67]
	v_lshl_add_u64 v[66:67], s[42:43], 1, v[66:67]
	v_lshl_add_u64 v[66:67], v[66:67], 0, v[180:181]
	v_lshl_add_u64 v[66:67], v[66:67], 0, v[180:181]
	v_pk_mul_f32 v[48:49], v[48:49], v[64:65] op_sel_hi:[1,0]
	v_pk_mul_f32 v[50:51], v[50:51], v[64:65] op_sel_hi:[1,0]
	v_pk_mul_f32 v[52:53], v[52:53], v[64:65] op_sel_hi:[1,0]
	v_pk_mul_f32 v[54:55], v[54:55], v[64:65] op_sel_hi:[1,0]
	v_cvt_pk_bf16_f32 v48, v48, v49
	v_cvt_pk_bf16_f32 v49, v50, v51
	v_cvt_pk_bf16_f32 v50, v52, v53
	v_cvt_pk_bf16_f32 v51, v54, v55
	v_pk_mul_f32 v[56:57], v[56:57], v[64:65] op_sel_hi:[1,0]
	v_pk_mul_f32 v[58:59], v[58:59], v[64:65] op_sel_hi:[1,0]
	v_pk_mul_f32 v[60:61], v[60:61], v[64:65] op_sel_hi:[1,0]
	v_pk_mul_f32 v[62:63], v[62:63], v[64:65] op_sel_hi:[1,0]
	v_permlane32_swap_b32 v48, v50
	v_permlane32_swap_b32 v49, v51
	global_store_dwordx4 v[66:67], v[48:51], off
	v_cvt_pk_bf16_f32 v52, v56, v57
	v_cvt_pk_bf16_f32 v53, v58, v59
	v_cvt_pk_bf16_f32 v54, v60, v61
	v_cvt_pk_bf16_f32 v55, v62, v63
	v_pk_mul_f32 v[32:33], v[32:33], v[64:65] op_sel_hi:[1,0]
	v_pk_mul_f32 v[34:35], v[34:35], v[64:65] op_sel_hi:[1,0]
	v_pk_mul_f32 v[36:37], v[36:37], v[64:65] op_sel_hi:[1,0]
	v_pk_mul_f32 v[38:39], v[38:39], v[64:65] op_sel_hi:[1,0]
	v_permlane32_swap_b32 v52, v54
	v_permlane32_swap_b32 v53, v55
	global_store_dwordx4 v[66:67], v[52:55], off offset:32
	v_cvt_pk_bf16_f32 v32, v32, v33
	v_cvt_pk_bf16_f32 v33, v34, v35
	v_cvt_pk_bf16_f32 v34, v36, v37
	v_cvt_pk_bf16_f32 v35, v38, v39
	v_pk_mul_f32 v[40:41], v[40:41], v[64:65] op_sel_hi:[1,0]
	v_pk_mul_f32 v[42:43], v[42:43], v[64:65] op_sel_hi:[1,0]
	v_pk_mul_f32 v[44:45], v[44:45], v[64:65] op_sel_hi:[1,0]
	v_pk_mul_f32 v[46:47], v[46:47], v[64:65] op_sel_hi:[1,0]
	v_permlane32_swap_b32 v32, v34
	v_permlane32_swap_b32 v33, v35
	global_store_dwordx4 v[66:67], v[32:35], off offset:64
	v_cvt_pk_bf16_f32 v36, v40, v41
	v_cvt_pk_bf16_f32 v37, v42, v43
	v_cvt_pk_bf16_f32 v38, v44, v45
	v_cvt_pk_bf16_f32 v39, v46, v47
	v_pk_mul_f32 v[16:17], v[16:17], v[64:65] op_sel_hi:[1,0]
	v_pk_mul_f32 v[18:19], v[18:19], v[64:65] op_sel_hi:[1,0]
	v_pk_mul_f32 v[20:21], v[20:21], v[64:65] op_sel_hi:[1,0]
	v_pk_mul_f32 v[22:23], v[22:23], v[64:65] op_sel_hi:[1,0]
	v_permlane32_swap_b32 v36, v38
	v_permlane32_swap_b32 v37, v39
	global_store_dwordx4 v[66:67], v[36:39], off offset:96
	v_cvt_pk_bf16_f32 v16, v16, v17
	v_cvt_pk_bf16_f32 v17, v18, v19
	v_cvt_pk_bf16_f32 v18, v20, v21
	v_cvt_pk_bf16_f32 v19, v22, v23
	v_pk_mul_f32 v[24:25], v[24:25], v[64:65] op_sel_hi:[1,0]
	v_pk_mul_f32 v[26:27], v[26:27], v[64:65] op_sel_hi:[1,0]
	v_pk_mul_f32 v[28:29], v[28:29], v[64:65] op_sel_hi:[1,0]
	v_pk_mul_f32 v[30:31], v[30:31], v[64:65] op_sel_hi:[1,0]
	v_permlane32_swap_b32 v16, v18
	v_permlane32_swap_b32 v17, v19
	global_store_dwordx4 v[66:67], v[16:19], off offset:128
	v_cvt_pk_bf16_f32 v20, v24, v25
	v_cvt_pk_bf16_f32 v21, v26, v27
	v_cvt_pk_bf16_f32 v22, v28, v29
	v_cvt_pk_bf16_f32 v23, v30, v31
	v_pk_mul_f32 v[0:1], v[0:1], v[64:65] op_sel_hi:[1,0]
	v_pk_mul_f32 v[2:3], v[2:3], v[64:65] op_sel_hi:[1,0]
	v_pk_mul_f32 v[4:5], v[4:5], v[64:65] op_sel_hi:[1,0]
	v_pk_mul_f32 v[6:7], v[6:7], v[64:65] op_sel_hi:[1,0]
	v_permlane32_swap_b32 v20, v22
	v_permlane32_swap_b32 v21, v23
	global_store_dwordx4 v[66:67], v[20:23], off offset:160
	v_cvt_pk_bf16_f32 v0, v0, v1
	v_cvt_pk_bf16_f32 v1, v2, v3
	v_cvt_pk_bf16_f32 v2, v4, v5
	v_cvt_pk_bf16_f32 v3, v6, v7
	v_pk_mul_f32 v[8:9], v[8:9], v[64:65] op_sel_hi:[1,0]
	v_pk_mul_f32 v[10:11], v[10:11], v[64:65] op_sel_hi:[1,0]
	v_pk_mul_f32 v[12:13], v[12:13], v[64:65] op_sel_hi:[1,0]
	v_pk_mul_f32 v[14:15], v[14:15], v[64:65] op_sel_hi:[1,0]
	v_permlane32_swap_b32 v0, v2
	v_permlane32_swap_b32 v1, v3
	global_store_dwordx4 v[66:67], v[0:3], off offset:192
	v_cvt_pk_bf16_f32 v4, v8, v9
	v_cvt_pk_bf16_f32 v5, v10, v11
	v_cvt_pk_bf16_f32 v6, v12, v13
	v_cvt_pk_bf16_f32 v7, v14, v15
	s_nop 1
	v_permlane32_swap_b32 v4, v6
	v_permlane32_swap_b32 v5, v7
	global_store_dwordx4 v[66:67], v[4:7], off offset:224
	s_add_i32 s21, s21, 1
	s_cmp_eq_u32 s21, 4
	s_cbranch_scc1 .LBB0_800
